# branch-GEMM epilogue de-serialisation: all 32 gate loads of a unit issued as one batch into spare registers (one round trip instead of four)
# speedup vs baseline: 1.0247x; 1.0173x over previous
;     __device__ __forceinline__ void operator()(f32x4 (&acc)[2][2][4][2], const Unit& u, int wr, int wc, int fr, int fq) const {
;     ...
;             for (int q = 0; q < 2; ++q) { const int m = 2 * mp2 + q; const size_t row = (size_t)(row0 + ai * HALF + m * 16); const unsigned char* gp = (const unsigned char*)G + row * 3072 + col0;
; #pragma unroll
;                 for (int bj = 0; bj < 2; ++bj) { ga[q][bj] = *(const u32x2q*)(gp + n * 1024 + bj * HALF); gb[q][bj] = *(const u32x2q*)(gp + nn * 1024 + bj * HALF); } }
;             asm volatile("" : "+v"(ga[0][0]), "+v"(ga[0][1]), "+v"(ga[1][0]), "+v"(ga[1][1]), "+v"(gb[0][0]), "+v"(gb[0][1]), "+v"(gb[1][0]), "+v"(gb[1][1]));
.LBB0_1041:
	s_lshl_b32 s0, s26, 8
	s_ashr_i32 s6, s26, 2
	s_and_b32 s0, s0, 0x300
	s_cmp_gt_i32 s6, 1
	s_cselect_b64 s[28:29], -1, 0
	s_cmp_lt_i32 s6, 2
	v_or_b32_e32 v0, s0, v180
	s_cselect_b64 s[0:1], -1, 0
	s_cmp_lg_u64 s[0:1], 0
	s_addc_u32 s0, s6, 0
	v_lshl_add_u32 v2, s24, 8, v178
	s_lshl_b32 s24, s6, 10
	s_lshl_b32 s26, s0, 10
	v_lshl_add_u64 v[144:145], s[12:13], 0, v[0:1]
	s_ashr_i32 s25, s24, 31
	s_ashr_i32 s27, s26, 31
	v_mad_i64_i32 v[146:147], s[0:1], v2, s56, v[144:145]
	v_lshl_add_u64 v[148:149], v[146:147], 0, s[24:25]
	v_lshl_add_u64 v[146:147], v[146:147], 0, s[26:27]
	v_or_b32_e32 v150, 16, v2
	global_load_dwordx2 v[156:157], v[148:149], off
	global_load_dwordx2 v[170:171], v[146:147], off
	global_load_dwordx2 v[158:159], v[146:147], off offset:128
	global_load_dwordx2 v[176:177], v[148:149], off offset:128
	v_mad_i64_i32 v[146:147], s[0:1], v150, s56, v[144:145]
	v_lshl_add_u64 v[152:153], v[146:147], 0, s[24:25]
	v_lshl_add_u64 v[146:147], v[146:147], 0, s[26:27]
	global_load_dwordx2 v[154:155], v[152:153], off
	global_load_dwordx2 v[148:149], v[146:147], off
	s_nop 0
	global_load_dwordx2 v[146:147], v[146:147], off offset:128
	s_nop 0
	global_load_dwordx2 v[152:153], v[152:153], off offset:128
	v_add_u32_e32 v217, 0x20, v2
	v_mad_i64_i32 v[252:253], s[0:1], v217, s56, v[144:145]
	v_lshl_add_u64 v[252:253], v[252:253], 0, s[24:25]
	global_load_dwordx2 v[192:193], v[252:253], off
	global_load_dwordx2 v[198:199], v[252:253], off offset:128
	v_mad_i64_i32 v[252:253], s[0:1], v217, s56, v[144:145]
	v_lshl_add_u64 v[252:253], v[252:253], 0, s[26:27]
	global_load_dwordx2 v[194:195], v[252:253], off
	global_load_dwordx2 v[196:197], v[252:253], off offset:128
	v_add_u32_e32 v217, 0x30, v2
	v_mad_i64_i32 v[252:253], s[0:1], v217, s56, v[144:145]
	v_lshl_add_u64 v[252:253], v[252:253], 0, s[24:25]
	global_load_dwordx2 v[200:201], v[252:253], off
	global_load_dwordx2 v[206:207], v[252:253], off offset:128
	v_mad_i64_i32 v[252:253], s[0:1], v217, s56, v[144:145]
	v_lshl_add_u64 v[252:253], v[252:253], 0, s[26:27]
	global_load_dwordx2 v[202:203], v[252:253], off
	global_load_dwordx2 v[204:205], v[252:253], off offset:128
	v_add_u32_e32 v217, 0x80, v2
	v_mad_i64_i32 v[252:253], s[0:1], v217, s56, v[144:145]
	v_lshl_add_u64 v[252:253], v[252:253], 0, s[24:25]
	global_load_dwordx2 v[208:209], v[252:253], off
	global_load_dwordx2 v[214:215], v[252:253], off offset:128
	v_mad_i64_i32 v[252:253], s[0:1], v217, s56, v[144:145]
	v_lshl_add_u64 v[252:253], v[252:253], 0, s[26:27]
	global_load_dwordx2 v[210:211], v[252:253], off
	global_load_dwordx2 v[212:213], v[252:253], off offset:128
	v_add_u32_e32 v217, 0x90, v2
	v_mad_i64_i32 v[252:253], s[0:1], v217, s56, v[144:145]
	v_lshl_add_u64 v[252:253], v[252:253], 0, s[24:25]
	global_load_dwordx2 v[220:221], v[252:253], off
	global_load_dwordx2 v[226:227], v[252:253], off offset:128
	v_mad_i64_i32 v[252:253], s[0:1], v217, s56, v[144:145]
	v_lshl_add_u64 v[252:253], v[252:253], 0, s[26:27]
	global_load_dwordx2 v[222:223], v[252:253], off
	global_load_dwordx2 v[224:225], v[252:253], off offset:128
	v_add_u32_e32 v217, 0xa0, v2
	v_mad_i64_i32 v[252:253], s[0:1], v217, s56, v[144:145]
	v_lshl_add_u64 v[252:253], v[252:253], 0, s[24:25]
	global_load_dwordx2 v[228:229], v[252:253], off
	global_load_dwordx2 v[236:237], v[252:253], off offset:128
	v_mad_i64_i32 v[252:253], s[0:1], v217, s56, v[144:145]
	v_lshl_add_u64 v[252:253], v[252:253], 0, s[26:27]
	global_load_dwordx2 v[230:231], v[252:253], off
	global_load_dwordx2 v[234:235], v[252:253], off offset:128
	v_add_u32_e32 v217, 0xb0, v2
	v_mad_i64_i32 v[252:253], s[0:1], v217, s56, v[144:145]
	v_lshl_add_u64 v[252:253], v[252:253], 0, s[24:25]
	global_load_dwordx2 v[244:245], v[252:253], off
	global_load_dwordx2 v[250:251], v[252:253], off offset:128
	v_mad_i64_i32 v[252:253], s[0:1], v217, s56, v[144:145]
	v_lshl_add_u64 v[252:253], v[252:253], 0, s[26:27]
	global_load_dwordx2 v[246:247], v[252:253], off
	global_load_dwordx2 v[248:249], v[252:253], off offset:128
	s_mov_b64 s[6:7], -1
	v_ashrrev_i32_e32 v3, 31, v2
	v_lshlrev_b32_e32 v0, 1, v0
	s_and_b64 vcc, exec, s[28:29]
	s_waitcnt vmcnt(0)
	s_nop 0
	v_cvt_f32_ubyte1_e32 v173, v156
	v_cvt_f32_ubyte0_e32 v172, v156
	v_cvt_f32_ubyte3_e32 v175, v156
	v_cvt_f32_ubyte2_e32 v174, v156
	v_cvt_f32_ubyte1_e32 v169, v157
	v_cvt_f32_ubyte0_e32 v168, v157
	v_cvt_f32_ubyte3_e32 v167, v157
	v_cvt_f32_ubyte2_e32 v166, v157
	v_cvt_f32_ubyte1_e32 v163, v176
	v_cvt_f32_ubyte0_e32 v162, v176
	v_cvt_f32_ubyte3_e32 v165, v176
	v_cvt_f32_ubyte2_e32 v164, v176
	v_cvt_f32_ubyte1_e32 v161, v177
	v_cvt_f32_ubyte0_e32 v160, v177
	v_cvt_f32_ubyte3_e32 v157, v177
	v_cvt_f32_ubyte2_e32 v156, v177
	s_cbranch_vccz .LBB0_1043
	s_mov_b32 s0, 0x3b808081
	v_pk_mul_f32 v[182:183], v[130:131], s[0:1] op_sel_hi:[1,0]
	v_pk_mul_f32 v[184:185], v[128:129], s[0:1] op_sel_hi:[1,0]
	v_lshlrev_b64 v[176:177], 11, v[2:3]
	v_pk_mul_f32 v[186:187], v[182:183], v[174:175]
	v_pk_mul_f32 v[182:183], v[184:185], v[172:173]
	v_pk_mul_f32 v[184:185], v[126:127], s[0:1] op_sel_hi:[1,0]
	v_pk_mul_f32 v[188:189], v[124:125], s[0:1] op_sel_hi:[1,0]
	v_lshl_add_u64 v[176:177], s[10:11], 0, v[176:177]
	v_pk_mul_f32 v[190:191], v[184:185], v[166:167]
	v_pk_mul_f32 v[184:185], v[188:189], v[168:169]
	v_lshl_add_u64 v[176:177], v[176:177], 0, v[0:1]
	v_cvt_pk_bf16_f32 v182, v182, v183
	v_cvt_pk_bf16_f32 v183, v186, v187
	v_cvt_pk_bf16_f32 v184, v184, v185
	v_cvt_pk_bf16_f32 v185, v190, v191
	global_store_dwordx4 v[176:177], v[182:185], off
	v_pk_mul_f32 v[188:189], v[92:93], s[0:1] op_sel_hi:[1,0]
	s_mov_b64 s[6:7], 0
	v_pk_mul_f32 v[182:183], v[98:99], s[0:1] op_sel_hi:[1,0]
	v_pk_mul_f32 v[184:185], v[96:97], s[0:1] op_sel_hi:[1,0]
	v_pk_mul_f32 v[186:187], v[182:183], v[164:165]
	v_pk_mul_f32 v[182:183], v[184:185], v[162:163]
	v_pk_mul_f32 v[184:185], v[94:95], s[0:1] op_sel_hi:[1,0]
	v_cvt_pk_bf16_f32 v182, v182, v183
	v_pk_mul_f32 v[190:191], v[184:185], v[156:157]
	v_pk_mul_f32 v[184:185], v[188:189], v[160:161]
	v_cvt_pk_bf16_f32 v183, v186, v187
	v_cvt_pk_bf16_f32 v184, v184, v185
	v_cvt_pk_bf16_f32 v185, v190, v191
	global_store_dwordx4 v[176:177], v[182:185], off offset:256

; __device__ __forceinline__ u32x4 pack8(f32x4 v0, f32x4 v1) { u32x4 w; w.x = cvt_pk_bf16(v0[0], v0[1]); w.y = cvt_pk_bf16(v0[2], v0[3]); w.z = cvt_pk_bf16(v1[0], v1[1]); w.w = cvt_pk_bf16(v1[2], v1[3]); return w; }
; __device__ __forceinline__ f32x4 dq4u8(unsigned w) { return (f32x4){(float)(w & 0xffu), (float)((w >> 8) & 0xffu), (float)((w >> 16) & 0xffu), (float)(w >> 24)}; }
;     __device__ __forceinline__ void operator()(f32x4 (&acc)[2][2][4][2], const Unit& u, int wr, int wc, int fr, int fq) const {
;     ...
;             for (int q = 0; q < 2; ++q) { const int m = 2 * mp2 + q; const size_t row = (size_t)(row0 + ai * HALF + m * 16); const unsigned char* gp = (const unsigned char*)G + row * 3072 + col0;
; #pragma unroll
;                 for (int bj = 0; bj < 2; ++bj) { ga[q][bj] = *(const u32x2q*)(gp + n * 1024 + bj * HALF); gb[q][bj] = *(const u32x2q*)(gp + nn * 1024 + bj * HALF); } }
;             asm volatile("" : "+v"(ga[0][0]), "+v"(ga[0][1]), "+v"(ga[1][0]), "+v"(ga[1][1]), "+v"(gb[0][0]), "+v"(gb[0][1]), "+v"(gb[1][0]), "+v"(gb[1][1]));
; #pragma unroll
;             for (int q = 0; q < 2; ++q) { const int m = 2 * mp2 + q; const size_t row = (size_t)(row0 + ai * HALF + m * 16);
;                 if (n < 2) {
; #pragma unroll
;                     for (int bj = 0; bj < 2; ++bj) { const f32x4 d0 = dq4u8(gb[q][bj].x), d1 = dq4u8(gb[q][bj].y);
;                         const f32x4 r0 = dq4u8(ga[q][bj].x) * (f32x4){__builtin_amdgcn_rcpf(d0[0]), __builtin_amdgcn_rcpf(d0[1]), __builtin_amdgcn_rcpf(d0[2]), __builtin_amdgcn_rcpf(d0[3])};
;                         const f32x4 r1 = dq4u8(ga[q][bj].y) * (f32x4){__builtin_amdgcn_rcpf(d1[0]), __builtin_amdgcn_rcpf(d1[1]), __builtin_amdgcn_rcpf(d1[2]), __builtin_amdgcn_rcpf(d1[3])};
;                         acc[ai][bj][m][0] *= r0; acc[ai][bj][m][1] *= r1; }
;                 } else { bf16_t* mp = MG + row * 1024 + col0;
; #pragma unroll
;                     for (int bj = 0; bj < 2; ++bj) *(u32x4*)(mp + bj * HALF) = pack8(dq4u8(ga[q][bj].x) * (acc[ai][bj][m][0] * (1.0f / 255.0f)), dq4u8(ga[q][bj].y) * (acc[ai][bj][m][1] * (1.0f / 255.0f))); } }
.LBB0_1049:
	v_or_b32_e32 v176, 32, v2
	v_mad_i64_i32 v[146:147], s[0:1], v176, s56, v[144:145]
	v_lshl_add_u64 v[148:149], v[146:147], 0, s[24:25]
	v_lshl_add_u64 v[146:147], v[146:147], 0, s[26:27]
	v_or_b32_e32 v150, 48, v2
	v_mov_b32_e32 v156, v192
	v_mov_b32_e32 v157, v193
	v_mov_b32_e32 v170, v194
	v_mov_b32_e32 v171, v195
	v_mov_b32_e32 v160, v196
	v_mov_b32_e32 v161, v197
	v_mov_b32_e32 v182, v198
	v_mov_b32_e32 v183, v199
	v_mad_i64_i32 v[146:147], s[0:1], v150, s56, v[144:145]
	v_lshl_add_u64 v[152:153], v[146:147], 0, s[24:25]
	v_lshl_add_u64 v[146:147], v[146:147], 0, s[26:27]
	v_mov_b32_e32 v154, v200
	v_mov_b32_e32 v155, v201
	v_mov_b32_e32 v148, v202
	v_mov_b32_e32 v149, v203
	s_nop 0
	v_mov_b32_e32 v146, v204
	v_mov_b32_e32 v147, v205
	s_nop 0
	v_mov_b32_e32 v152, v206
	v_mov_b32_e32 v153, v207
	s_mov_b64 s[28:29], -1
	s_and_b64 vcc, exec, s[6:7]
	s_waitcnt vmcnt(0)
	s_nop 0
	v_cvt_f32_ubyte1_e32 v173, v156
	v_cvt_f32_ubyte0_e32 v172, v156
	v_cvt_f32_ubyte3_e32 v175, v156
	v_cvt_f32_ubyte2_e32 v174, v156
	v_cvt_f32_ubyte1_e32 v169, v157
	v_cvt_f32_ubyte0_e32 v168, v157
	v_cvt_f32_ubyte3_e32 v167, v157
	v_cvt_f32_ubyte2_e32 v166, v157
	v_cvt_f32_ubyte1_e32 v163, v182
	v_cvt_f32_ubyte0_e32 v162, v182
	v_cvt_f32_ubyte3_e32 v165, v182
	v_cvt_f32_ubyte2_e32 v164, v182
	v_cvt_f32_ubyte1_e32 v159, v183
	v_cvt_f32_ubyte0_e32 v158, v183
	v_cvt_f32_ubyte3_e32 v157, v183
	v_cvt_f32_ubyte2_e32 v156, v183
	s_cbranch_vccnz .LBB0_1051
	s_mov_b32 s0, 0x3b808081
	v_ashrrev_i32_e32 v177, 31, v176
	v_pk_mul_f32 v[182:183], v[114:115], s[0:1] op_sel_hi:[1,0]
	v_pk_mul_f32 v[184:185], v[112:113], s[0:1] op_sel_hi:[1,0]
	v_lshlrev_b64 v[176:177], 11, v[176:177]
	v_pk_mul_f32 v[186:187], v[182:183], v[174:175]
	v_pk_mul_f32 v[182:183], v[184:185], v[172:173]
	v_pk_mul_f32 v[184:185], v[110:111], s[0:1] op_sel_hi:[1,0]
	v_pk_mul_f32 v[188:189], v[108:109], s[0:1] op_sel_hi:[1,0]
	v_lshl_add_u64 v[176:177], s[10:11], 0, v[176:177]
	v_pk_mul_f32 v[190:191], v[184:185], v[166:167]
	v_pk_mul_f32 v[184:185], v[188:189], v[168:169]
	v_lshl_add_u64 v[176:177], v[176:177], 0, v[0:1]
	v_cvt_pk_bf16_f32 v182, v182, v183
	v_cvt_pk_bf16_f32 v183, v186, v187
	v_cvt_pk_bf16_f32 v184, v184, v185
	v_cvt_pk_bf16_f32 v185, v190, v191
	global_store_dwordx4 v[176:177], v[182:185], off
	v_pk_mul_f32 v[188:189], v[76:77], s[0:1] op_sel_hi:[1,0]
	s_mov_b64 s[28:29], 0
	v_pk_mul_f32 v[182:183], v[82:83], s[0:1] op_sel_hi:[1,0]
	v_pk_mul_f32 v[184:185], v[80:81], s[0:1] op_sel_hi:[1,0]
	v_pk_mul_f32 v[186:187], v[182:183], v[164:165]
	v_pk_mul_f32 v[182:183], v[184:185], v[162:163]
	v_pk_mul_f32 v[184:185], v[78:79], s[0:1] op_sel_hi:[1,0]
	v_cvt_pk_bf16_f32 v182, v182, v183
	v_pk_mul_f32 v[190:191], v[184:185], v[156:157]
	v_pk_mul_f32 v[184:185], v[188:189], v[158:159]
	v_cvt_pk_bf16_f32 v183, v186, v187
	v_cvt_pk_bf16_f32 v184, v184, v185
	v_cvt_pk_bf16_f32 v185, v190, v191
	global_store_dwordx4 v[176:177], v[182:185], off offset:256

; __device__ __forceinline__ u32x4 pack8(f32x4 v0, f32x4 v1) { u32x4 w; w.x = cvt_pk_bf16(v0[0], v0[1]); w.y = cvt_pk_bf16(v0[2], v0[3]); w.z = cvt_pk_bf16(v1[0], v1[1]); w.w = cvt_pk_bf16(v1[2], v1[3]); return w; }
; __device__ __forceinline__ f32x4 dq4u8(unsigned w) { return (f32x4){(float)(w & 0xffu), (float)((w >> 8) & 0xffu), (float)((w >> 16) & 0xffu), (float)(w >> 24)}; }
;     __device__ __forceinline__ void operator()(f32x4 (&acc)[2][2][4][2], const Unit& u, int wr, int wc, int fr, int fq) const {
;     ...
;             for (int q = 0; q < 2; ++q) { const int m = 2 * mp2 + q; const size_t row = (size_t)(row0 + ai * HALF + m * 16); const unsigned char* gp = (const unsigned char*)G + row * 3072 + col0;
; #pragma unroll
;                 for (int bj = 0; bj < 2; ++bj) { ga[q][bj] = *(const u32x2q*)(gp + n * 1024 + bj * HALF); gb[q][bj] = *(const u32x2q*)(gp + nn * 1024 + bj * HALF); } }
;             asm volatile("" : "+v"(ga[0][0]), "+v"(ga[0][1]), "+v"(ga[1][0]), "+v"(ga[1][1]), "+v"(gb[0][0]), "+v"(gb[0][1]), "+v"(gb[1][0]), "+v"(gb[1][1]));
; #pragma unroll
;             for (int q = 0; q < 2; ++q) { const int m = 2 * mp2 + q; const size_t row = (size_t)(row0 + ai * HALF + m * 16);
;                 if (n < 2) {
; #pragma unroll
;                     for (int bj = 0; bj < 2; ++bj) { const f32x4 d0 = dq4u8(gb[q][bj].x), d1 = dq4u8(gb[q][bj].y);
;                         const f32x4 r0 = dq4u8(ga[q][bj].x) * (f32x4){__builtin_amdgcn_rcpf(d0[0]), __builtin_amdgcn_rcpf(d0[1]), __builtin_amdgcn_rcpf(d0[2]), __builtin_amdgcn_rcpf(d0[3])};
;                         const f32x4 r1 = dq4u8(ga[q][bj].y) * (f32x4){__builtin_amdgcn_rcpf(d1[0]), __builtin_amdgcn_rcpf(d1[1]), __builtin_amdgcn_rcpf(d1[2]), __builtin_amdgcn_rcpf(d1[3])};
;                         acc[ai][bj][m][0] *= r0; acc[ai][bj][m][1] *= r1; }
;                 } else { bf16_t* mp = MG + row * 1024 + col0;
; #pragma unroll
;                     for (int bj = 0; bj < 2; ++bj) *(u32x4*)(mp + bj * HALF) = pack8(dq4u8(ga[q][bj].x) * (acc[ai][bj][m][0] * (1.0f / 255.0f)), dq4u8(ga[q][bj].y) * (acc[ai][bj][m][1] * (1.0f / 255.0f))); } }
.LBB0_1057:
	v_add_u32_e32 v176, 0x80, v2
	v_mad_i64_i32 v[146:147], s[0:1], v176, s56, v[144:145]
	v_lshl_add_u64 v[148:149], v[146:147], 0, s[24:25]
	v_lshl_add_u64 v[146:147], v[146:147], 0, s[26:27]
	v_add_u32_e32 v150, 0x90, v2
	v_mov_b32_e32 v156, v208
	v_mov_b32_e32 v157, v209
	v_mov_b32_e32 v170, v210
	v_mov_b32_e32 v171, v211
	v_mov_b32_e32 v160, v212
	v_mov_b32_e32 v161, v213
	v_mov_b32_e32 v182, v214
	v_mov_b32_e32 v183, v215
	v_mad_i64_i32 v[146:147], s[0:1], v150, s56, v[144:145]
	v_lshl_add_u64 v[152:153], v[146:147], 0, s[24:25]
	v_lshl_add_u64 v[146:147], v[146:147], 0, s[26:27]
	v_mov_b32_e32 v154, v220
	v_mov_b32_e32 v155, v221
	v_mov_b32_e32 v148, v222
	v_mov_b32_e32 v149, v223
	s_nop 0
	v_mov_b32_e32 v146, v224
	v_mov_b32_e32 v147, v225
	s_nop 0
	v_mov_b32_e32 v152, v226
	v_mov_b32_e32 v153, v227
	s_mov_b64 s[28:29], -1
	s_and_b64 vcc, exec, s[6:7]
	s_waitcnt vmcnt(0)
	s_nop 0
	v_cvt_f32_ubyte1_e32 v173, v156
	v_cvt_f32_ubyte0_e32 v172, v156
	v_cvt_f32_ubyte3_e32 v175, v156
	v_cvt_f32_ubyte2_e32 v174, v156
	v_cvt_f32_ubyte1_e32 v169, v157
	v_cvt_f32_ubyte0_e32 v168, v157
	v_cvt_f32_ubyte3_e32 v167, v157
	v_cvt_f32_ubyte2_e32 v166, v157
	v_cvt_f32_ubyte1_e32 v163, v182
	v_cvt_f32_ubyte0_e32 v162, v182
	v_cvt_f32_ubyte3_e32 v165, v182
	v_cvt_f32_ubyte2_e32 v164, v182
	v_cvt_f32_ubyte1_e32 v159, v183
	v_cvt_f32_ubyte0_e32 v158, v183
	v_cvt_f32_ubyte3_e32 v157, v183
	v_cvt_f32_ubyte2_e32 v156, v183
	s_cbranch_vccnz .LBB0_1059
	s_mov_b32 s0, 0x3b808081
	v_ashrrev_i32_e32 v177, 31, v176
	v_pk_mul_f32 v[182:183], v[66:67], s[0:1] op_sel_hi:[1,0]
	v_pk_mul_f32 v[184:185], v[64:65], s[0:1] op_sel_hi:[1,0]
	v_lshlrev_b64 v[176:177], 11, v[176:177]
	v_pk_mul_f32 v[186:187], v[182:183], v[174:175]
	v_pk_mul_f32 v[182:183], v[184:185], v[172:173]
	v_pk_mul_f32 v[184:185], v[62:63], s[0:1] op_sel_hi:[1,0]
	v_pk_mul_f32 v[188:189], v[60:61], s[0:1] op_sel_hi:[1,0]
	v_lshl_add_u64 v[176:177], s[10:11], 0, v[176:177]
	v_pk_mul_f32 v[190:191], v[184:185], v[166:167]
	v_pk_mul_f32 v[184:185], v[188:189], v[168:169]
	v_lshl_add_u64 v[176:177], v[176:177], 0, v[0:1]
	v_cvt_pk_bf16_f32 v182, v182, v183
	v_cvt_pk_bf16_f32 v183, v186, v187
	v_cvt_pk_bf16_f32 v184, v184, v185
	v_cvt_pk_bf16_f32 v185, v190, v191
	global_store_dwordx4 v[176:177], v[182:185], off
	v_pk_mul_f32 v[188:189], v[28:29], s[0:1] op_sel_hi:[1,0]
	s_mov_b64 s[28:29], 0
	v_pk_mul_f32 v[182:183], v[34:35], s[0:1] op_sel_hi:[1,0]
	v_pk_mul_f32 v[184:185], v[32:33], s[0:1] op_sel_hi:[1,0]
	v_pk_mul_f32 v[186:187], v[182:183], v[164:165]
	v_pk_mul_f32 v[182:183], v[184:185], v[162:163]
	v_pk_mul_f32 v[184:185], v[30:31], s[0:1] op_sel_hi:[1,0]
	v_cvt_pk_bf16_f32 v182, v182, v183
	v_pk_mul_f32 v[190:191], v[184:185], v[156:157]
	v_pk_mul_f32 v[184:185], v[188:189], v[158:159]
	v_cvt_pk_bf16_f32 v183, v186, v187
	v_cvt_pk_bf16_f32 v184, v184, v185
	v_cvt_pk_bf16_f32 v185, v190, v191
	global_store_dwordx4 v[176:177], v[182:185], off offset:256

; __device__ __forceinline__ u32x4 pack8(f32x4 v0, f32x4 v1) { u32x4 w; w.x = cvt_pk_bf16(v0[0], v0[1]); w.y = cvt_pk_bf16(v0[2], v0[3]); w.z = cvt_pk_bf16(v1[0], v1[1]); w.w = cvt_pk_bf16(v1[2], v1[3]); return w; }
; __device__ __forceinline__ f32x4 dq4u8(unsigned w) { return (f32x4){(float)(w & 0xffu), (float)((w >> 8) & 0xffu), (float)((w >> 16) & 0xffu), (float)(w >> 24)}; }
;     __device__ __forceinline__ void operator()(f32x4 (&acc)[2][2][4][2], const Unit& u, int wr, int wc, int fr, int fq) const {
;     ...
;             for (int q = 0; q < 2; ++q) { const int m = 2 * mp2 + q; const size_t row = (size_t)(row0 + ai * HALF + m * 16); const unsigned char* gp = (const unsigned char*)G + row * 3072 + col0;
; #pragma unroll
;                 for (int bj = 0; bj < 2; ++bj) { ga[q][bj] = *(const u32x2q*)(gp + n * 1024 + bj * HALF); gb[q][bj] = *(const u32x2q*)(gp + nn * 1024 + bj * HALF); } }
;             asm volatile("" : "+v"(ga[0][0]), "+v"(ga[0][1]), "+v"(ga[1][0]), "+v"(ga[1][1]), "+v"(gb[0][0]), "+v"(gb[0][1]), "+v"(gb[1][0]), "+v"(gb[1][1]));
; #pragma unroll
;             for (int q = 0; q < 2; ++q) { const int m = 2 * mp2 + q; const size_t row = (size_t)(row0 + ai * HALF + m * 16);
;                 if (n < 2) {
; #pragma unroll
;                     for (int bj = 0; bj < 2; ++bj) { const f32x4 d0 = dq4u8(gb[q][bj].x), d1 = dq4u8(gb[q][bj].y);
;                         const f32x4 r0 = dq4u8(ga[q][bj].x) * (f32x4){__builtin_amdgcn_rcpf(d0[0]), __builtin_amdgcn_rcpf(d0[1]), __builtin_amdgcn_rcpf(d0[2]), __builtin_amdgcn_rcpf(d0[3])};
;                         const f32x4 r1 = dq4u8(ga[q][bj].y) * (f32x4){__builtin_amdgcn_rcpf(d1[0]), __builtin_amdgcn_rcpf(d1[1]), __builtin_amdgcn_rcpf(d1[2]), __builtin_amdgcn_rcpf(d1[3])};
;                         acc[ai][bj][m][0] *= r0; acc[ai][bj][m][1] *= r1; }
;                 } else { bf16_t* mp = MG + row * 1024 + col0;
; #pragma unroll
;                     for (int bj = 0; bj < 2; ++bj) *(u32x4*)(mp + bj * HALF) = pack8(dq4u8(ga[q][bj].x) * (acc[ai][bj][m][0] * (1.0f / 255.0f)), dq4u8(ga[q][bj].y) * (acc[ai][bj][m][1] * (1.0f / 255.0f))); } }
.LBB0_1065:
	v_add_u32_e32 v172, 0xa0, v2
	v_mad_i64_i32 v[146:147], s[0:1], v172, s56, v[144:145]
	v_lshl_add_u64 v[148:149], v[146:147], 0, s[24:25]
	v_lshl_add_u64 v[146:147], v[146:147], 0, s[26:27]
	v_mov_b32_e32 v152, v228
	v_mov_b32_e32 v153, v229
	v_mov_b32_e32 v166, v230
	v_mov_b32_e32 v167, v231
	v_mov_b32_e32 v156, v234
	v_mov_b32_e32 v157, v235
	v_mov_b32_e32 v174, v236
	v_mov_b32_e32 v175, v237
	v_add_u32_e32 v146, 0xb0, v2
	v_mad_i64_i32 v[2:3], s[0:1], v146, s56, v[144:145]
	v_lshl_add_u64 v[148:149], v[2:3], 0, s[24:25]
	v_lshl_add_u64 v[2:3], v[2:3], 0, s[26:27]
	v_mov_b32_e32 v150, v244
	v_mov_b32_e32 v151, v245
	v_mov_b32_e32 v144, v246
	v_mov_b32_e32 v145, v247
	s_nop 0
	v_mov_b32_e32 v2, v248
	v_mov_b32_e32 v3, v249
	s_nop 0
	v_mov_b32_e32 v148, v250
	v_mov_b32_e32 v149, v251
	s_mov_b64 s[24:25], -1
	s_and_b64 vcc, exec, s[6:7]
	s_waitcnt vmcnt(0)
	s_nop 0
	v_cvt_f32_ubyte1_e32 v169, v152
	v_cvt_f32_ubyte0_e32 v168, v152
	v_cvt_f32_ubyte3_e32 v171, v152
	v_cvt_f32_ubyte2_e32 v170, v152
	v_cvt_f32_ubyte1_e32 v165, v153
	v_cvt_f32_ubyte0_e32 v164, v153
	v_cvt_f32_ubyte3_e32 v163, v153
	v_cvt_f32_ubyte2_e32 v162, v153
	v_cvt_f32_ubyte1_e32 v159, v174
	v_cvt_f32_ubyte0_e32 v158, v174
	v_cvt_f32_ubyte3_e32 v161, v174
	v_cvt_f32_ubyte2_e32 v160, v174
	v_cvt_f32_ubyte1_e32 v155, v175
	v_cvt_f32_ubyte0_e32 v154, v175
	v_cvt_f32_ubyte3_e32 v153, v175
	v_cvt_f32_ubyte2_e32 v152, v175
	s_cbranch_vccnz .LBB0_1067
	v_ashrrev_i32_e32 v173, 31, v172
	v_lshlrev_b64 v[172:173], 11, v[172:173]
	v_lshl_add_u64 v[172:173], s[10:11], 0, v[172:173]
	s_mov_b32 s0, 0x3b808081
	v_lshl_add_u64 v[176:177], v[172:173], 0, v[0:1]
	v_pk_mul_f32 v[172:173], v[50:51], s[0:1] op_sel_hi:[1,0]
	v_pk_mul_f32 v[174:175], v[48:49], s[0:1] op_sel_hi:[1,0]
	v_pk_mul_f32 v[182:183], v[172:173], v[170:171]
	v_pk_mul_f32 v[172:173], v[174:175], v[168:169]
	v_pk_mul_f32 v[174:175], v[46:47], s[0:1] op_sel_hi:[1,0]
	v_pk_mul_f32 v[184:185], v[44:45], s[0:1] op_sel_hi:[1,0]
	v_pk_mul_f32 v[186:187], v[174:175], v[162:163]
	v_pk_mul_f32 v[174:175], v[184:185], v[164:165]
	v_cvt_pk_bf16_f32 v172, v172, v173
	v_cvt_pk_bf16_f32 v173, v182, v183
	v_cvt_pk_bf16_f32 v174, v174, v175
	v_cvt_pk_bf16_f32 v175, v186, v187
	global_store_dwordx4 v[176:177], v[172:175], off
	v_pk_mul_f32 v[184:185], v[12:13], s[0:1] op_sel_hi:[1,0]
	s_mov_b64 s[24:25], 0
	v_pk_mul_f32 v[172:173], v[18:19], s[0:1] op_sel_hi:[1,0]
	v_pk_mul_f32 v[174:175], v[16:17], s[0:1] op_sel_hi:[1,0]
	v_pk_mul_f32 v[182:183], v[172:173], v[160:161]
	v_pk_mul_f32 v[172:173], v[174:175], v[158:159]
	v_pk_mul_f32 v[174:175], v[14:15], s[0:1] op_sel_hi:[1,0]
	v_cvt_pk_bf16_f32 v172, v172, v173
	v_pk_mul_f32 v[186:187], v[174:175], v[152:153]
	v_pk_mul_f32 v[174:175], v[184:185], v[154:155]
	v_cvt_pk_bf16_f32 v173, v182, v183
	v_cvt_pk_bf16_f32 v174, v174, v175
	v_cvt_pk_bf16_f32 v175, v186, v187
	global_store_dwordx4 v[176:177], v[172:175], off offset:256
